# P1 schedule: memory K/V tiles (slow transposing epilogue) moved to the 5th round of their workgroups; displaced in-proj tiles become 6th round of WGs 80-143; conversion slots follow
# speedup vs baseline: 1.0128x; 1.0128x over previous
.LBB0_125:
	s_add_i32 s56, s56, 1
	s_mul_i32 s69, s56, s26
	s_add_i32 s69, s69, s2
	s_cmpk_lg_i32 s26, 0x100
	s_cbranch_scc1 .Lp1_nomap
	s_sub_i32 s12, s69, 0x410
	s_cmp_lt_u32 s12, 64
	s_cbranch_scc0 .Lp1_m1
	s_add_i32 s69, s69, 0x100
	s_branch .Lp1_nomap
.Lp1_m1:
	s_sub_i32 s12, s69, 0x510
	s_cmp_lt_u32 s12, 64
	s_cbranch_scc0 .Lp1_m2
	s_movk_i32 s69, 0x2000
	s_branch .Lp1_nomap
.Lp1_m2:
	s_sub_i32 s12, s69, 0x550
	s_cmp_lt_u32 s12, 64
	s_cbranch_scc0 .Lp1_nomap
	s_sub_i32 s69, s69, 0x140
.Lp1_nomap:
	s_cmpk_gt_i32 s69, 0x54f
	s_cselect_b64 s[40:41], -1, 0
	s_and_b64 vcc, exec, s[40:41]
	s_cbranch_vccnz .LBB0_131
	s_cmpk_gt_i32 s69, 0x50f
	s_mov_b64 s[48:49], -1
	s_cbranch_scc0 .LBB0_128
	s_add_i32 s12, s69, 0xfffffaf0
	s_and_b32 s45, s69, 3
	s_lshr_b32 s43, s12, 2
	s_or_b32 s42, s45, 36
	s_add_i32 s44, s43, 36
	s_mov_b64 s[48:49], 0

.LBB0_237:
	s_abs_i32 s78, s26
	v_cvt_f32_u32_e32 v0, s78
	s_add_i32 s3, s26, 0x54f
	s_ashr_i32 s6, s26, 31
	s_sub_i32 s4, 0xfffffab1, s26
	v_rcp_iflag_f32_e32 v0, v0
	s_ashr_i32 s5, s3, 31
	s_max_i32 s3, s3, s4
	s_sub_i32 s4, 0, s78
	v_mul_f32_e32 v0, 0x4f7ffffe, v0
	v_cvt_u32_f32_e32 v0, v0
	v_writelane_b32 v226, s6, 5
	s_xor_b32 s5, s5, s6
	v_readfirstlane_b32 s6, v0
	s_mul_i32 s4, s4, s6
	s_mul_hi_u32 s4, s6, s4
	s_add_i32 s4, s6, s4
	v_writelane_b32 v226, s4, 6
	s_mul_hi_u32 s4, s3, s4
	s_mul_i32 s6, s4, s78
	s_sub_i32 s3, s3, s6
	s_add_i32 s7, s4, 1
	s_sub_i32 s6, s3, s78
	s_cmp_ge_u32 s3, s78
	s_cselect_b32 s4, s7, s4
	s_cselect_b32 s3, s6, s3
	s_add_i32 s6, s4, 1
	s_cmp_ge_u32 s3, s78
	s_cselect_b32 s3, s6, s4
	s_xor_b32 s3, s3, s5
	s_not_b32 s4, s5
	s_add_i32 s3, s4, s3
	s_mul_i32 s3, s3, s26
	s_sub_i32 s3, 0x550, s3
	s_cmp_lg_u32 s26, s3
	s_cselect_b32 s4, s3, 0
	s_sub_i32 s3, s2, s4
	s_cmpk_lg_i32 s26, 0x100
	s_cbranch_scc1 .Lp1_slot_done
	s_sub_i32 s9, s2, 16
	s_cmp_lt_u32 s9, 64
	s_cbranch_scc0 .Lp1_slot_b
	s_mov_b32 s3, s9
	s_branch .Lp1_slot_done
.Lp1_slot_b:
	s_sub_i32 s9, s2, 0x50
	s_cmp_lt_u32 s9, 64
	s_cbranch_scc0 .Lp1_slot_done
	s_mov_b32 s3, -1
.Lp1_slot_done:
	s_cmp_lt_i32 s3, 0
	s_cbranch_scc1 .LBB0_275
	s_lshl_b32 s3, s3, 3
	s_add_i32 s3, s77, s3
	s_addk_i32 s3, 0x3400
	s_cmpk_gt_i32 s3, 0x53ff
	s_cbranch_scc1 .LBB0_275
	v_lshlrev_b32_e32 v1, 3, v166
	s_sub_i32 s4, s26, s4
	v_bfe_u32 v5, v166, 3, 3
	v_and_b32_e32 v6, 56, v1
	s_lshl_b32 s14, s4, 3
	v_bfe_u32 v0, v166, 5, 1
	v_and_b32_e32 v2, 31, v166
	v_mov_b32_e32 v3, 0
	v_readlane_b32 s4, v226, 0
	v_mul_u32_u24_e32 v1, 0x84, v6
	v_lshlrev_b32_e32 v7, 2, v5
	v_lshl_add_u32 v4, v2, 2, s4
	s_movk_i32 s15, 0x84
	v_add3_u32 v10, s4, v1, v7
	v_or_b32_e32 v11, 8, v5
	v_or_b32_e32 v12, 16, v5
	v_or_b32_e32 v13, 24, v5
	v_mov_b32_e32 v1, v0
	v_lshlrev_b32_e32 v2, 2, v2
	v_lshlrev_b32_e32 v6, 1, v6
	v_mov_b32_e32 v7, v3
